# P6 unit queue order: memory-prompt, then memory/sliding-window SAMPLE units (long single-wave units), then sliding-window prompt units last, so the long units no longer form the phase tail
# speedup vs baseline: 1.0031x; 1.0031x over previous
.LBB0_1291:
	s_or_b64 exec, exec, s[0:1]
	s_waitcnt lgkmcnt(0)
	s_barrier
	ds_read_b32 v0, v170
	s_movk_i32 s0, 0x34f
	s_waitcnt lgkmcnt(0)
	s_barrier
	v_cmp_lt_u32_e64 s[4:5], s0, v0
	v_readfirstlane_b32 s89, v0
	s_and_b64 vcc, exec, s[4:5]
	s_cbranch_vccnz .LBB0_1286
	s_sub_i32 s99, s89, 0x100
	s_cmp_lt_u32 s99, 0x250
	s_cbranch_scc0 .Lq6_no
	s_cmp_lt_u32 s99, 80
	s_cbranch_scc0 .Lq6_w
	s_add_i32 s89, s89, 0x200
	s_branch .Lq6_no
.Lq6_w:
	s_sub_i32 s89, s89, 80
.Lq6_no:
	v_sub_co_u32_e64 v0, s[6:7], s89, v171
	s_nop 0
	v_readfirstlane_b32 s91, v0
	s_cmp_lt_u32 s91, 0xfffffe00
	s_cselect_b64 s[0:1], -1, 0
	s_or_b64 s[8:9], s[0:1], s[78:79]
	s_or_b64 s[10:11], s[6:7], s[16:17]
	s_and_b64 s[8:9], s[8:9], s[10:11]
	s_and_b64 vcc, exec, s[8:9]
	s_cbranch_vccnz .LBB0_1307
	s_and_saveexec_b64 s[8:9], s[96:97]
	s_cbranch_execz .LBB0_1306
	s_and_b64 s[10:11], s[0:1], exec
	s_cselect_b32 s10, 64, 0
	s_add_u32 s10, s22, s10
	s_addc_u32 s11, s23, 0
	global_load_dword v0, v161, s[10:11] offset:1536 sc1
	s_and_b64 s[12:13], s[0:1], exec
	s_cselect_b32 s14, 0xc0, 64
	s_waitcnt vmcnt(0)
	v_cmp_le_u32_e32 vcc, s14, v0
	s_cbranch_vccnz .LBB0_1305
	s_mov_b32 s15, 0xfffff8
	s_branch .LBB0_1297

	.amdhsa_kernel _Z8yoco_fwd4Args
		.amdhsa_group_segment_fixed_size 0
		.amdhsa_private_segment_fixed_size 0
		.amdhsa_kernarg_size 464
		.amdhsa_user_sgpr_count 2
		.amdhsa_user_sgpr_dispatch_ptr 0
		.amdhsa_user_sgpr_queue_ptr 0
		.amdhsa_user_sgpr_kernarg_segment_ptr 1
		.amdhsa_user_sgpr_dispatch_id 0
		.amdhsa_user_sgpr_kernarg_preload_length 0
		.amdhsa_user_sgpr_kernarg_preload_offset 0
		.amdhsa_user_sgpr_private_segment_size 0
		.amdhsa_uses_dynamic_stack 0
		.amdhsa_enable_private_segment 0
		.amdhsa_system_sgpr_workgroup_id_x 1
		.amdhsa_system_sgpr_workgroup_id_y 0
		.amdhsa_system_sgpr_workgroup_id_z 0
		.amdhsa_system_sgpr_workgroup_info 0
		.amdhsa_system_vgpr_workitem_id 2
		.amdhsa_next_free_vgpr 256
		.amdhsa_next_free_sgpr 100
		.amdhsa_accum_offset 256
		.amdhsa_reserve_vcc 1
		.amdhsa_float_round_mode_32 0
		.amdhsa_float_round_mode_16_64 0
		.amdhsa_float_denorm_mode_32 3
		.amdhsa_float_denorm_mode_16_64 3
		.amdhsa_dx10_clamp 1
		.amdhsa_ieee_mode 1
		.amdhsa_fp16_overflow 0
		.amdhsa_tg_split 0
		.amdhsa_exception_fp_ieee_invalid_op 0
		.amdhsa_exception_fp_denorm_src 0
		.amdhsa_exception_fp_ieee_div_zero 0
		.amdhsa_exception_fp_ieee_overflow 0
		.amdhsa_exception_fp_ieee_underflow 0
		.amdhsa_exception_fp_ieee_inexact 0
		.amdhsa_exception_int_div_zero 0
	.end_amdhsa_kernel

amdhsa.kernels:
  - .agpr_count:     0
    .args:
      - .offset:         0
        .size:           208
        .value_kind:     by_value
      - .offset:         208
        .size:           4
        .value_kind:     hidden_block_count_x
      - .offset:         212
        .size:           4
        .value_kind:     hidden_block_count_y
      - .offset:         216
        .size:           4
        .value_kind:     hidden_block_count_z
      - .offset:         220
        .size:           2
        .value_kind:     hidden_group_size_x
      - .offset:         222
        .size:           2
        .value_kind:     hidden_group_size_y
      - .offset:         224
        .size:           2
        .value_kind:     hidden_group_size_z
      - .offset:         226
        .size:           2
        .value_kind:     hidden_remainder_x
      - .offset:         228
        .size:           2
        .value_kind:     hidden_remainder_y
      - .offset:         230
        .size:           2
        .value_kind:     hidden_remainder_z
      - .offset:         248
        .size:           8
        .value_kind:     hidden_global_offset_x
      - .offset:         256
        .size:           8
        .value_kind:     hidden_global_offset_y
      - .offset:         264
        .size:           8
        .value_kind:     hidden_global_offset_z
      - .offset:         272
        .size:           2
        .value_kind:     hidden_grid_dims
      - .offset:         296
        .size:           8
        .value_kind:     hidden_multigrid_sync_arg
      - .offset:         328
        .size:           4
        .value_kind:     hidden_dynamic_lds_size
    .group_segment_fixed_size: 0
    .kernarg_segment_align: 8
    .kernarg_segment_size: 464
    .language:       OpenCL C
    .language_version:
      - 2
      - 0
    .max_flat_workgroup_size: 512
    .name:           _Z8yoco_fwd4Args
    .private_segment_fixed_size: 0
    .sgpr_count:     106
    .sgpr_spill_count: 195
    .symbol:         _Z8yoco_fwd4Args.kd
    .uniform_work_group_size: 1
    .uses_dynamic_stack: false
    .vgpr_count:     256
    .vgpr_spill_count: 0
    .wavefront_size: 64
